# attention main loop duplicated per wave half: waves 0-3 stage the rotary-key slice unconditionally, waves 4-7 carry no rotary-key staging or exec masking
# speedup vs baseline: 1.0107x; 1.0038x over previous
; template <int KB, bool HASY>
; __device__ __forceinline__ void phaseA(f32x16& X0, f32x16& X1, f32x16& Y0, f32x16& Y1, bf16x8& pa0, bf16x8& pa1, bf16x8& pa2, bf16x8& pa3,
;                                        const bf16x8* qr, const f32x16& negm, int kaddr, VFr& vf, int vb, float& l_reg) {
;   SBAR();
;   float ls = 0.f;
;   bf16x8 k0 = rd128<KOFF(KB, 0, 0)>(kaddr), k1 = rd128<KOFF(KB, 1, 0)>(kaddr), k2 = rd128<KOFF(KB, 0, 1)>(kaddr), k3 = rd128<KOFF(KB, 1, 1)>(kaddr);
;   if (HASY) { EXP4(Y0, 0); EXP4(Y0, 4); }
;   SBAR(); WAIT4(k0, k1, k2, k3);
;   bf16x8 k4 = rd128<KOFF(KB, 0, 2)>(kaddr), k5 = rd128<KOFF(KB, 1, 2)>(kaddr), k6 = rd128<KOFF(KB, 0, 3)>(kaddr), k7 = rd128<KOFF(KB, 1, 3)>(kaddr);
;   SBAR();
;   X0 = MF(k0, qr[0], negm); if (HASY) { EXP4(Y0, 8); SUM4(Y0, 0); } SBAR();
;   X1 = MF(k1, qr[0], negm); if (HASY) { EXP4(Y0, 12); SUM4(Y0, 4); } SBAR();
;   X0 = MF(k2, qr[1], X0); if (HASY) { PACK8(Y0, 0, pa0); } SBAR();
;   X1 = MF(k3, qr[1], X1); if (HASY) { EXP4(Y1, 0); SUM4(Y0, 8); } SBAR();
;   WAIT4(k4, k5, k6, k7);
;   bf16x8 k8 = rd128<KOFF(KB, 0, 4)>(kaddr), k9 = rd128<KOFF(KB, 1, 4)>(kaddr), k10 = rd128<KOFF(KB, 0, 5)>(kaddr), k11 = rd128<KOFF(KB, 1, 5)>(kaddr);
;   SBAR();
;   X0 = MF(k4, qr[2], X0); if (HASY) { EXP4(Y1, 4); SUM4(Y0, 12); } SBAR();
;   X1 = MF(k5, qr[2], X1); if (HASY) { PACK8(Y0, 8, pa1); } SBAR();
; __device__ __forceinline__ void attn_unit(const bf16_t* __restrict__ Qb, const bf16_t* __restrict__ KNh, const bf16_t* __restrict__ KRb, const bf16_t* __restrict__ Vh,
;                                           bf16_t* __restrict__ Ob, int nkeys, char* lds, int tid_in) {
;     ...
;   f32x16 pA0, pA1, pB0, pB1; float alA, alB; bf16x8 pa0, pa1, pa2, pa3; VFr vf; const int NT = nkeys / KVBLK;
;   constexpr int SE = 0, SO = 1;
;   int vprev = 0, vcur = SHM_V, vnext = 2 * SHM_V;
;     ...
;   SLOAD(SE, 0); asm volatile("s_waitcnt vmcnt(0)" ::: "memory"); SWRITE(0, 0, SE); __syncthreads();
;   phaseA<0, false>(pA0, pA1, pB0, pB1, pa0, pa1, pa2, pa3, qr, negm, kaddr, vf, vb0, l_reg);
;   alA = decide<true>(rowmax32(pA0, pA1), pA0, pA1, m_reg, negm);
;   SLOAD(SO, KVBLK); if (2 < NT) SLOAD(SE, 2 * KVBLK);
;   SWAIT(); SWRITE(1, SHM_V, SO); __syncthreads();
;   for (int j = 1; j + 1 < NT; j += 2) {
;     phaseA<1, true>(pB0, pB1, pA0, pA1, pa0, pa1, pa2, pa3, qr, negm, kaddr, vf, vb0 + vprev, l_reg);
.LBB0_244:
	s_or_b64 exec, exec, s[18:19]
	s_waitcnt vmcnt(3)
	s_waitcnt vmcnt(3)
	ds_write_b128 v187, v[34:37] offset:8192
	s_waitcnt vmcnt(2)
	ds_write_b128 v188, v[38:41] offset:37888
	v_add_u32_e32 v34, v45, v44
	s_and_saveexec_b64 s[18:19], vcc
	s_xor_b64 s[18:19], exec, s[18:19]
	v_add_u32_e32 v34, v45, v44
	s_andn2_saveexec_b64 s[18:19], s[18:19]
	v_add_u32_e32 v35, 0, v34
	ds_write_b128 v35, v[158:161] offset:38016
	s_or_b64 exec, exec, s[18:19]
	v_max_f32_e32 v36, v46, v46
	v_max_f32_e32 v0, v0, v0
	v_and_b32_e32 v35, 63, v42
	v_max_f32_e32 v0, v0, v36
	v_sub_f32_e32 v67, v3, v0
	v_lshlrev_b32_e32 v3, 4, v35
	v_sub_f32_e32 v68, v4, v0
	v_sub_f32_e32 v66, v2, v0
	v_lshlrev_b32_e32 v2, 3, v35
	v_and_b32_e32 v3, 0xc0, v3
	v_lshlrev_b32_e32 v4, 1, v35
	v_add_f32_e32 v189, 0, v0
	v_sub_f32_e32 v97, v33, v0
	v_sub_f32_e32 v96, v32, v0
	v_sub_f32_e32 v95, v31, v0
	v_sub_f32_e32 v94, v30, v0
	v_sub_f32_e32 v93, v29, v0
	v_sub_f32_e32 v92, v28, v0
	v_sub_f32_e32 v91, v27, v0
	v_sub_f32_e32 v90, v26, v0
	v_sub_f32_e32 v89, v25, v0
	v_sub_f32_e32 v88, v24, v0
	v_sub_f32_e32 v87, v23, v0
	v_sub_f32_e32 v86, v22, v0
	v_sub_f32_e32 v85, v21, v0
	v_sub_f32_e32 v84, v20, v0
	v_sub_f32_e32 v83, v19, v0
	v_sub_f32_e32 v82, v18, v0
	v_sub_f32_e32 v81, v17, v0
	v_sub_f32_e32 v80, v16, v0
	v_sub_f32_e32 v79, v15, v0
	v_sub_f32_e32 v78, v14, v0
	v_sub_f32_e32 v77, v13, v0
	v_sub_f32_e32 v76, v12, v0
	v_sub_f32_e32 v75, v11, v0
	v_sub_f32_e32 v74, v10, v0
	v_sub_f32_e32 v73, v9, v0
	v_sub_f32_e32 v72, v8, v0
	v_sub_f32_e32 v71, v7, v0
	v_sub_f32_e32 v70, v6, v0
	v_sub_f32_e32 v69, v5, v0
	v_and_b32_e32 v0, 0x3fffffc0, v42
	v_and_or_b32 v3, v2, 24, v3
	v_and_b32_e32 v4, 32, v4
	v_and_b32_e32 v2, 0x100, v2
	s_cmp_lg_u32 0, -1
	v_lshl_add_u32 v0, v0, 2, 0
	v_or3_b32 v2, v3, v4, v2
	s_cselect_b32 s19, 0, 0
	v_mov_b32_e32 v14, v1
	v_mov_b32_e32 v15, v1
	v_add_u32_e32 v192, s19, v2
	v_lshl_add_u32 v183, v182, 2, v0
	v_lshl_add_u32 v179, v181, 4, v0
	v_mov_b32_e32 v0, v1
	v_mov_b32_e32 v2, v1
	v_mov_b32_e32 v3, v1
	v_mov_b32_e32 v4, v1
	v_mov_b32_e32 v5, v1
	v_mov_b32_e32 v6, v1
	v_mov_b32_e32 v7, v1
	v_mov_b32_e32 v8, v1
	v_mov_b32_e32 v9, v1
	v_mov_b32_e32 v10, v1
	v_mov_b32_e32 v11, v1
	v_mov_b32_e32 v12, v1
	v_mov_b32_e32 v13, v1
	v_mov_b64_e32 v[32:33], v[14:15]
	v_xor_b32_e32 v50, 0x80000000, v189
	v_mov_b64_e32 v[30:31], v[12:13]
	v_mov_b64_e32 v[28:29], v[10:11]
	v_mov_b64_e32 v[26:27], v[8:9]
	v_mov_b64_e32 v[24:25], v[6:7]
	v_mov_b64_e32 v[22:23], v[4:5]
	v_mov_b64_e32 v[20:21], v[2:3]
	v_mov_b64_e32 v[18:19], v[0:1]
	v_mov_b64_e32 v[16:17], v[14:15]
	v_and_b32_e32 v178, 0xffffffe0, v43
	s_mov_b32 s39, 4
	s_mov_b32 s18, 0
	v_cmp_gt_u32_e64 s[40:41], 32, v35
	v_mov_b32_e32 v194, 0
	s_movk_i32 s53, 0x2000
	s_mov_b32 s52, 0x8000
	s_movk_i32 s68, 0x4000
	v_add_u32_e32 v193, 0, v34
	v_mov_b64_e32 v[14:15], v[12:13]
	v_mov_b64_e32 v[12:13], v[10:11]
	v_mov_b64_e32 v[10:11], v[8:9]
	v_mov_b64_e32 v[8:9], v[6:7]
	v_mov_b64_e32 v[6:7], v[4:5]
	v_mov_b64_e32 v[4:5], v[2:3]
	v_mov_b64_e32 v[2:3], v[0:1]
	s_movk_i32 s69, 0x4000
	v_mov_b32_e32 v51, v50
	v_mov_b32_e32 v52, v50
	v_mov_b32_e32 v53, v50
	v_mov_b32_e32 v54, v50
	v_mov_b32_e32 v55, v50
	v_mov_b32_e32 v56, v50
	v_mov_b32_e32 v57, v50
	v_mov_b32_e32 v58, v50
	v_mov_b32_e32 v59, v50
	v_mov_b32_e32 v60, v50
	v_mov_b32_e32 v61, v50
	v_mov_b32_e32 v62, v50
	v_mov_b32_e32 v63, v50
	v_mov_b32_e32 v64, v50
	v_mov_b32_e32 v65, v50
	s_waitcnt lgkmcnt(0)
	s_barrier
	s_cmp_lg_u64 s[42:43], 0
	s_cbranch_scc0 .Lmy_y249
.LBB0_249:
	s_mov_b32 s76, s53
	s_mov_b32 s53, s18
	v_add_u32_e32 v0, s53, v192
	ds_read_b128 v[34:37], v184 offset:0x3400
	ds_read_b128 v[38:41], v184 offset:0x4e00
	ds_read_b128 v[42:45], v184 offset:0x3420
	ds_read_b128 v[46:49], v184 offset:0x4e20
	ds_read_b128 v[170:173], v184 offset:0x3440
	ds_read_b128 v[174:177], v184 offset:0x4e40
	ds_read_b128 v[204:207], v184 offset:0x3460
	ds_read_b128 v[208:211], v184 offset:0x4e60
	v_exp_f32_e32 v82, v82
	v_exp_f32_e32 v195, v83
	v_exp_f32_e32 v84, v84
	v_exp_f32_e32 v196, v85
	v_exp_f32_e32 v83, v86
	v_exp_f32_e32 v85, v87
	v_exp_f32_e32 v86, v88
	v_exp_f32_e32 v87, v89
	s_waitcnt lgkmcnt(7)
	v_mfma_f32_32x32x16_bf16 v[114:129], v[34:37], v[150:153], v[50:65]
	v_exp_f32_e32 v88, v90
	v_exp_f32_e32 v89, v91
	v_exp_f32_e32 v90, v92
	v_exp_f32_e32 v91, v93
	s_waitcnt lgkmcnt(6)
	v_mfma_f32_32x32x16_bf16 v[98:113], v[38:41], v[150:153], v[50:65]
	v_exp_f32_e32 v92, v94
	v_exp_f32_e32 v93, v95
	v_exp_f32_e32 v94, v96
	v_exp_f32_e32 v95, v97
	s_waitcnt lgkmcnt(5)
	v_mfma_f32_32x32x16_bf16 v[114:129], v[42:45], v[146:149], v[114:129]
	v_cvt_pk_bf16_f32 v34, v82, v195
	v_cvt_pk_bf16_f32 v35, v84, v196
	v_cvt_pk_bf16_f32 v36, v83, v85
	v_cvt_pk_bf16_f32 v37, v86, v87
	s_waitcnt lgkmcnt(4)
	v_mfma_f32_32x32x16_bf16 v[98:113], v[46:49], v[146:149], v[98:113]
	v_exp_f32_e32 v96, v66
	v_exp_f32_e32 v97, v67
	v_exp_f32_e32 v197, v68
	v_exp_f32_e32 v198, v69
	ds_read_b128 v[38:41], v184 offset:0x3480
	ds_read_b128 v[66:69], v184 offset:0x4e80
	ds_read_b128 v[212:215], v184 offset:0x34a0
	ds_read_b128 v[216:219], v184 offset:0x4ea0
	s_waitcnt lgkmcnt(4)
	v_mfma_f32_32x32x16_bf16 v[114:129], v[170:173], v[142:145], v[114:129]
	v_exp_f32_e32 v199, v70
	v_exp_f32_e32 v200, v71
	v_exp_f32_e32 v201, v72
	v_exp_f32_e32 v202, v73
	v_mfma_f32_32x32x16_bf16 v[98:113], v[174:177], v[142:145], v[98:113]
	v_cvt_pk_bf16_f32 v42, v88, v89
	v_cvt_pk_bf16_f32 v43, v90, v91
	v_cvt_pk_bf16_f32 v44, v92, v93
	v_cvt_pk_bf16_f32 v45, v94, v95
	v_mfma_f32_32x32x16_bf16 v[114:129], v[204:207], v[138:141], v[114:129]
	v_exp_f32_e32 v203, v74
	v_exp_f32_e32 v204, v75
	v_exp_f32_e32 v205, v76
	v_exp_f32_e32 v206, v77
	v_mfma_f32_32x32x16_bf16 v[98:113], v[208:211], v[138:141], v[98:113]
	v_exp_f32_e32 v207, v78
	v_exp_f32_e32 v208, v79
	v_exp_f32_e32 v209, v80
	v_exp_f32_e32 v210, v81
	s_waitcnt lgkmcnt(0)
; #define SBAR() __builtin_amdgcn_sched_barrier(0)
; #define MX3(a, b, c) __builtin_fmaxf(__builtin_fmaxf((a), (b)), (c))
; #define MF(A, B, C) __builtin_amdgcn_mfma_f32_32x32x16_bf16(A, B, C, 0, 0, 0)
; #define VWAIT(f) asm volatile("s_waitcnt lgkmcnt(0)" : "+v"(f.a0), "+v"(f.b0), "+v"(f.c0), "+v"(f.d0), "+v"(f.a1), "+v"(f.b1), "+v"(f.c1), "+v"(f.d1) :: "memory")
; #define SWAIT() do { asm volatile("s_waitcnt vmcnt(3)" ::: "memory"); } while (0)
; template <bool HASX>
; __device__ __forceinline__ float phaseB(f32x16* o, bf16x8 pa0, bf16x8 pa1, bf16x8 pa2, bf16x8 pa3, VFr& f, int vb, const f32x16& X0, const f32x16& X1) {
;   SBAR(); VWAIT(f); VFr g; vfr_issue<2>(g, vb); SBAR();
;   float a = 0.f, b = 0.f;
;   o[0] = MF(pa0, PKV(f.a0, f.b0), o[0]); SBAR(); o[1] = MF(pa0, PKV(f.c0, f.d0), o[1]);
;   if (HASX) { a = MX3(X0[0], X0[1], X1[0]); b = MX3(X0[2], X0[3], X1[1]); a = MX3(a, X1[2], X1[3]); b = MX3(b, X0[4], X0[5]); } SBAR();
;   o[0] = MF(pa1, PKV(f.a1, f.b1), o[0]); if (HASX) { a = MX3(a, X0[6], X0[7]); b = MX3(b, X1[4], X1[5]); } SBAR();
;   o[1] = MF(pa1, PKV(f.c1, f.d1), o[1]); if (HASX) { a = MX3(a, X1[6], X1[7]); b = MX3(b, X0[8], X0[9]); a = MX3(a, X0[10], X0[11]); } SBAR();
;   VWAIT(g); SBAR();
;   o[0] = MF(pa2, PKV(g.a0, g.b0), o[0]); if (HASX) { b = MX3(b, X1[8], X1[9]); a = MX3(a, X1[10], X1[11]); } SBAR();
;   o[1] = MF(pa2, PKV(g.c0, g.d0), o[1]); if (HASX) { b = MX3(b, X0[12], X0[13]); a = MX3(a, X0[14], X0[15]); } SBAR();
;   o[0] = MF(pa3, PKV(g.a1, g.b1), o[0]); if (HASX) { b = MX3(b, X1[12], X1[13]); a = MX3(a, X1[14], X1[15]); } SBAR();
;   o[1] = MF(pa3, PKV(g.c1, g.d1), o[1]); SBAR();
;   float pmax = __builtin_fmaxf(a, b);
;   if (HASX) { auto rr = __builtin_amdgcn_permlane32_swap(__float_as_uint(pmax), __float_as_uint(pmax), false, false); pmax = __builtin_fmaxf(__uint_as_float(rr[0]), __uint_as_float(rr[1])); }
;   return pmax;
; }
; __device__ __forceinline__ void attn_unit(const bf16_t* __restrict__ Qb, const bf16_t* __restrict__ KNh, const bf16_t* __restrict__ KRb, const bf16_t* __restrict__ Vh,
;                                           bf16_t* __restrict__ Ob, int nkeys, char* lds, int tid_in) {
;     ...
;     SLOAD(SO, (j + 2) * KVBLK); SBAR();
;     alB = decide<false>(phaseB<true>(o, pa0, pa1, pa2, pa3, vf, vb0 + vprev, pB0, pB1), pB0, pB1, m_reg, negm);
;     SWAIT(); SWRITE(0, vnext, SE);
	s_nop 0
	v_mfma_f32_32x32x16_bf16 v[114:129], v[38:41], v[134:137], v[114:129]
	v_cvt_pk_bf16_f32 v46, v96, v97
	v_cvt_pk_bf16_f32 v47, v197, v198
	v_cvt_pk_bf16_f32 v48, v199, v200
	v_cvt_pk_bf16_f32 v49, v201, v202
	v_mfma_f32_32x32x16_bf16 v[98:113], v[66:69], v[134:137], v[98:113]
	v_mfma_f32_32x32x16_bf16 v[114:129], v[212:215], v[130:133], v[114:129]
	v_cvt_pk_bf16_f32 v38, v203, v204
	v_cvt_pk_bf16_f32 v39, v205, v206
	v_cvt_pk_bf16_f32 v40, v207, v208
	v_cvt_pk_bf16_f32 v41, v209, v210
	ds_read_b64_tr_b16 v[78:79], v0 offset:0
	ds_read_b64_tr_b16 v[80:81], v0 offset:0x400
	ds_read_b64_tr_b16 v[74:75], v0 offset:0x200
	v_mfma_f32_32x32x16_bf16 v[98:113], v[216:219], v[130:133], v[98:113]
	ds_read_b64_tr_b16 v[76:77], v0 offset:0x600
	ds_read_b64_tr_b16 v[70:71], v0 offset:0x800
	ds_read_b64_tr_b16 v[72:73], v0 offset:0xc00
	ds_read_b64_tr_b16 v[66:67], v0 offset:0xa00
	ds_read_b64_tr_b16 v[68:69], v0 offset:0xe00
	s_add_i32 s18, s52, 0xffffe000
	s_mov_b32 s46, s66
	s_mov_b32 s47, s67
	buffer_load_dwordx4 v[170:173], v185, s[64:67], s18 offen
	buffer_load_dwordx4 v[174:177], v185, s[44:47], s18 offen
	s_add_i32 s28, s68, 0xfffff000
	buffer_load_dwordx4 v[158:161], v186, s[60:63], s28 offen
	s_waitcnt lgkmcnt(0)
	ds_read_b64_tr_b16 v[212:213], v0 offset:0x1000
	ds_read_b64_tr_b16 v[214:215], v0 offset:0x1400
	ds_read_b64_tr_b16 v[216:217], v0 offset:0x1200
	ds_read_b64_tr_b16 v[218:219], v0 offset:0x1600
	ds_read_b64_tr_b16 v[220:221], v0 offset:0x1800
	ds_read_b64_tr_b16 v[222:223], v0 offset:0x1c00
	ds_read_b64_tr_b16 v[228:229], v0 offset:0x1a00
	ds_read_b64_tr_b16 v[230:231], v0 offset:0x1e00
	s_nop 0
	v_mfma_f32_32x32x16_bf16 v[18:33], v[34:37], v[78:81], v[18:33]
	v_add_f32_e32 v238, v82, v195
	v_add_f32_e32 v239, v84, v196
	v_add_f32_e32 v240, v83, v85
	v_add_f32_e32 v241, v86, v87
	v_add_f32_e32 v238, v238, v239
	v_add_f32_e32 v240, v240, v241
	v_mfma_f32_32x32x16_bf16 v[2:17], v[34:37], v[74:77], v[2:17]
	v_max_f32_e32 v34, v114, v115
	v_max3_f32 v35, v116, v117, v99
	v_max3_f32 v34, v34, v98, v100
	v_max3_f32 v35, v35, v118, v119
	v_mfma_f32_32x32x16_bf16 v[18:33], v[42:45], v[70:73], v[18:33]
	v_max3_f32 v34, v34, v101, v120
	v_max3_f32 v35, v35, v102, v103
	v_add_f32_e32 v238, v240, v238
	v_add_f32_e32 v239, v88, v89
	v_add_f32_e32 v241, v90, v91
	v_mfma_f32_32x32x16_bf16 v[2:17], v[42:45], v[66:69], v[2:17]
	v_max3_f32 v34, v34, v121, v104
	v_max3_f32 v34, v34, v105, v124
	v_max3_f32 v35, v35, v122, v123
	v_add_f32_e32 v239, v239, v241
	v_add_f32_e32 v240, v92, v93
	v_add_f32_e32 v241, v94, v95
	s_waitcnt lgkmcnt(0)
	s_nop 0
	v_mfma_f32_32x32x16_bf16 v[18:33], v[46:49], v[212:215], v[18:33]
	v_max3_f32 v34, v34, v125, v108
	v_max3_f32 v35, v35, v106, v107
	v_add_f32_e32 v238, v239, v238
	v_add_f32_e32 v240, v240, v241
	s_waitcnt vmcnt(3)
	v_add_u32_e32 v67, s69, v187
	ds_write_b128 v67, v[162:165]
	v_mfma_f32_32x32x16_bf16 v[2:17], v[46:49], v[216:219], v[2:17]
	v_max3_f32 v34, v34, v109, v128
	v_max3_f32 v35, v35, v126, v127
	v_add_f32_e32 v238, v240, v238
	v_add_f32_e32 v239, v96, v97
	v_add_f32_e32 v241, v197, v198
	s_waitcnt vmcnt(2)
	ds_write_b128 v188, v[166:169] offset:24576
	v_mfma_f32_32x32x16_bf16 v[18:33], v[38:41], v[220:223], v[18:33]
	v_max3_f32 v34, v34, v129, v112
	v_max3_f32 v35, v35, v110, v111
	v_add_f32_e32 v239, v239, v241
	v_add_f32_e32 v240, v199, v200
	v_add_f32_e32 v241, v201, v202
	ds_write_b128 v193, v[154:157] offset:24704
	v_add_f32_e32 v238, v239, v238
	v_add_f32_e32 v240, v240, v241
	v_mfma_f32_32x32x16_bf16 v[2:17], v[38:41], v[228:231], v[2:17]
	v_max3_f32 v34, v34, v113, v35
	v_cmp_lt_f32_e32 vcc, s35, v34
	v_add_f32_e32 v238, v240, v238
	v_add_f32_e32 v239, v203, v204
	v_add_f32_e32 v241, v205, v206
	v_add_f32_e32 v239, v239, v241
	v_add_f32_e32 v240, v207, v208
	v_add_f32_e32 v241, v209, v210
	v_add_f32_e32 v238, v239, v238
	v_add_f32_e32 v240, v240, v241
	v_add_f32_e32 v238, v240, v238
	v_add_f32_e32 v194, v194, v238
	s_cbranch_vccnz .LBB0_272
; #define SBAR() __builtin_amdgcn_sched_barrier(0)
; #define MF(A, B, C) __builtin_amdgcn_mfma_f32_32x32x16_bf16(A, B, C, 0, 0, 0)
; template <int KB, bool HASY>
; __device__ __forceinline__ void phaseA(f32x16& X0, f32x16& X1, f32x16& Y0, f32x16& Y1, bf16x8& pa0, bf16x8& pa1, bf16x8& pa2, bf16x8& pa3,
;                                        const bf16x8* qr, const f32x16& negm, int kaddr, VFr& vf, int vb, float& l_reg) {
;   SBAR();
;   float ls = 0.f;
;   bf16x8 k0 = rd128<KOFF(KB, 0, 0)>(kaddr), k1 = rd128<KOFF(KB, 1, 0)>(kaddr), k2 = rd128<KOFF(KB, 0, 1)>(kaddr), k3 = rd128<KOFF(KB, 1, 1)>(kaddr);
;   if (HASY) { EXP4(Y0, 0); EXP4(Y0, 4); }
;   SBAR(); WAIT4(k0, k1, k2, k3);
;   bf16x8 k4 = rd128<KOFF(KB, 0, 2)>(kaddr), k5 = rd128<KOFF(KB, 1, 2)>(kaddr), k6 = rd128<KOFF(KB, 0, 3)>(kaddr), k7 = rd128<KOFF(KB, 1, 3)>(kaddr);
;   SBAR();
;   X0 = MF(k0, qr[0], negm); if (HASY) { EXP4(Y0, 8); SUM4(Y0, 0); } SBAR();
;   X1 = MF(k1, qr[0], negm); if (HASY) { EXP4(Y0, 12); SUM4(Y0, 4); } SBAR();
;   X0 = MF(k2, qr[1], X0); if (HASY) { PACK8(Y0, 0, pa0); } SBAR();
;   X1 = MF(k3, qr[1], X1); if (HASY) { EXP4(Y1, 0); SUM4(Y0, 8); } SBAR();
;   WAIT4(k4, k5, k6, k7);
;   bf16x8 k8 = rd128<KOFF(KB, 0, 4)>(kaddr), k9 = rd128<KOFF(KB, 1, 4)>(kaddr), k10 = rd128<KOFF(KB, 0, 5)>(kaddr), k11 = rd128<KOFF(KB, 1, 5)>(kaddr);
;   SBAR();
;   X0 = MF(k4, qr[2], X0); if (HASY) { EXP4(Y1, 4); SUM4(Y0, 12); } SBAR();
;   X1 = MF(k5, qr[2], X1); if (HASY) { PACK8(Y0, 8, pa1); } SBAR();
;   X0 = MF(k6, qr[3], X0); if (HASY) { EXP4(Y1, 8); SUM4(Y1, 0); } SBAR();
;   X1 = MF(k7, qr[3], X1); if (HASY) { EXP4(Y1, 12); SUM4(Y1, 4); } SBAR();
;   WAIT4(k8, k9, k10, k11);
;   SBAR();
;   X0 = MF(k8, qr[4], X0); if (HASY) { PACK8(Y1, 0, pa2); } SBAR();
;   X1 = MF(k9, qr[4], X1); if (HASY) { SUM4(Y1, 8); SUM4(Y1, 12); } SBAR();
;   X0 = MF(k10, qr[5], X0); if (HASY) { PACK8(Y1, 8, pa3); } SBAR();
;   X1 = MF(k11, qr[5], X1); if (HASY) vfr_issue<0>(vf, vb);
; __device__ __forceinline__ void attn_unit(const bf16_t* __restrict__ Qb, const bf16_t* __restrict__ KNh, const bf16_t* __restrict__ KRb, const bf16_t* __restrict__ Vh,
;                                           bf16_t* __restrict__ Ob, int nkeys, char* lds, int tid_in) {
;     ...
;     phaseA<0, true>(pA0, pA1, pB0, pB1, pa0, pa1, pa2, pa3, qr, negm, kaddr, vf, vb0 + vprev, l_reg);
;     if (j + 3 < NT) SLOAD(SE, (j + 3) * KVBLK); SBAR();
.LBB0_259:
	v_add_u32_e32 v237, s76, v192
	s_waitcnt lgkmcnt(0)
	s_barrier
	ds_read_b128 v[66:69], v184 offset:0
	ds_read_b128 v[212:215], v184 offset:0x1a00
	ds_read_b128 v[216:219], v184 offset:32
	v_exp_f32_e32 v195, v114
	v_exp_f32_e32 v197, v115
	v_exp_f32_e32 v198, v116
	v_exp_f32_e32 v201, v117
	v_exp_f32_e32 v196, v118
	v_exp_f32_e32 v199, v119
	v_exp_f32_e32 v200, v120
	v_exp_f32_e32 v202, v121
	ds_read_b128 v[118:121], v184 offset:0x1a20
	ds_read_b128 v[220:223], v184 offset:64
	ds_read_b128 v[228:231], v184 offset:0x1a40
	ds_read_b128 v[238:241], v184 offset:0x60
	ds_read_b128 v[242:245], v184 offset:0x1a60
	s_waitcnt lgkmcnt(7)
	v_mfma_f32_32x32x16_bf16 v[82:97], v[66:69], v[150:153], v[50:65]
	v_exp_f32_e32 v203, v122
	v_exp_f32_e32 v204, v123
	v_exp_f32_e32 v205, v124
	v_exp_f32_e32 v206, v125
	s_waitcnt lgkmcnt(6)
	v_mfma_f32_32x32x16_bf16 v[66:81], v[212:215], v[150:153], v[50:65]
	v_exp_f32_e32 v207, v126
	v_exp_f32_e32 v208, v127
	v_exp_f32_e32 v209, v128
	v_exp_f32_e32 v210, v129
	s_waitcnt lgkmcnt(5)
	v_mfma_f32_32x32x16_bf16 v[82:97], v[216:219], v[146:149], v[82:97]
	v_cvt_pk_bf16_f32 v114, v195, v197
	v_cvt_pk_bf16_f32 v115, v198, v201
	v_cvt_pk_bf16_f32 v116, v196, v199
	v_cvt_pk_bf16_f32 v117, v200, v202
	s_waitcnt lgkmcnt(4)
	v_mfma_f32_32x32x16_bf16 v[66:81], v[118:121], v[146:149], v[66:81]
	v_exp_f32_e32 v211, v98
	v_exp_f32_e32 v212, v99
	v_exp_f32_e32 v213, v100
	v_exp_f32_e32 v214, v101
	ds_read_b128 v[98:101], v184 offset:0x80
	ds_read_b128 v[118:121], v184 offset:0x1a80
	ds_read_b128 v[122:125], v184 offset:0xa0
	ds_read_b128 v[246:249], v184 offset:0x1aa0
	s_waitcnt lgkmcnt(4)
	v_mfma_f32_32x32x16_bf16 v[82:97], v[220:223], v[142:145], v[82:97]
	v_exp_f32_e32 v215, v102
	v_exp_f32_e32 v216, v103
	v_exp_f32_e32 v217, v104
	v_exp_f32_e32 v218, v105
	v_mfma_f32_32x32x16_bf16 v[66:81], v[228:231], v[142:145], v[66:81]
	v_cvt_pk_bf16_f32 v102, v203, v204
	v_cvt_pk_bf16_f32 v103, v205, v206
	v_cvt_pk_bf16_f32 v104, v207, v208
	v_cvt_pk_bf16_f32 v105, v209, v210
	v_mfma_f32_32x32x16_bf16 v[82:97], v[238:241], v[138:141], v[82:97]
	v_exp_f32_e32 v219, v106
	v_exp_f32_e32 v220, v107
	v_exp_f32_e32 v221, v108
	v_exp_f32_e32 v222, v109
	v_mfma_f32_32x32x16_bf16 v[66:81], v[242:245], v[138:141], v[66:81]
	v_exp_f32_e32 v223, v110
	v_exp_f32_e32 v234, v111
	v_exp_f32_e32 v235, v112
	v_exp_f32_e32 v236, v113
	s_waitcnt lgkmcnt(0)
	s_nop 0
	v_mfma_f32_32x32x16_bf16 v[82:97], v[98:101], v[134:137], v[82:97]
	v_cvt_pk_bf16_f32 v106, v211, v212
	v_cvt_pk_bf16_f32 v107, v213, v214
	v_cvt_pk_bf16_f32 v108, v215, v216
	v_cvt_pk_bf16_f32 v109, v217, v218
	v_mfma_f32_32x32x16_bf16 v[66:81], v[118:121], v[134:137], v[66:81]
	v_mfma_f32_32x32x16_bf16 v[82:97], v[122:125], v[130:133], v[82:97]
	v_cvt_pk_bf16_f32 v98, v219, v220
	v_cvt_pk_bf16_f32 v99, v221, v222
	v_cvt_pk_bf16_f32 v100, v223, v234
	v_cvt_pk_bf16_f32 v101, v235, v236
	ds_read_b64_tr_b16 v[126:127], v237 offset:0
	ds_read_b64_tr_b16 v[128:129], v237 offset:0x400
	ds_read_b64_tr_b16 v[122:123], v237 offset:0x200
	v_mfma_f32_32x32x16_bf16 v[66:81], v[246:249], v[130:133], v[66:81]
	ds_read_b64_tr_b16 v[124:125], v237 offset:0x600
	ds_read_b64_tr_b16 v[118:119], v237 offset:0x800
	ds_read_b64_tr_b16 v[120:121], v237 offset:0xc00
	ds_read_b64_tr_b16 v[110:111], v237 offset:0xa00
	ds_read_b64_tr_b16 v[112:113], v237 offset:0xe00
	s_cmp_ge_u32 s39, s38
	s_cselect_b64 s[18:19], -1, 0
	s_and_b64 vcc, exec, s[18:19]
	s_cbranch_vccnz .LBB0_263
	s_mov_b32 s46, s66
	s_mov_b32 s47, s67
	buffer_load_dwordx4 v[162:165], v185, s[64:67], s52 offen
	buffer_load_dwordx4 v[166:169], v185, s[44:47], s52 offen
	buffer_load_dwordx4 v[154:157], v186, s[60:63], s68 offen

; #define SBAR() __builtin_amdgcn_sched_barrier(0)
; #define MX3(a, b, c) __builtin_fmaxf(__builtin_fmaxf((a), (b)), (c))
; #define MF(A, B, C) __builtin_amdgcn_mfma_f32_32x32x16_bf16(A, B, C, 0, 0, 0)
; #define SWRITE(b, voff, i) do { *(bf16x8*)(V_lds + (voff) + vst0) = sr_[i].vs; *(bf16x8*)(K_lds + (b) * SHM_K + kst0) = sr_[i].ks; \
;     if (krt) *(bf16x8*)(K_lds + (b) * SHM_K + kst1) = sr_[i].kr; } while (0)
; #define SWAIT() do { asm volatile("s_waitcnt vmcnt(3)" ::: "memory"); } while (0)
; template <bool HASX>
; __device__ __forceinline__ float phaseB(f32x16* o, bf16x8 pa0, bf16x8 pa1, bf16x8 pa2, bf16x8 pa3, VFr& f, int vb, const f32x16& X0, const f32x16& X1) {
;     ...
;   o[0] = MF(pa2, PKV(g.a0, g.b0), o[0]); if (HASX) { b = MX3(b, X1[8], X1[9]); a = MX3(a, X1[10], X1[11]); } SBAR();
;   o[1] = MF(pa2, PKV(g.c0, g.d0), o[1]); if (HASX) { b = MX3(b, X0[12], X0[13]); a = MX3(a, X0[14], X0[15]); } SBAR();
;   o[0] = MF(pa3, PKV(g.a1, g.b1), o[0]); if (HASX) { b = MX3(b, X1[12], X1[13]); a = MX3(a, X1[14], X1[15]); } SBAR();
;   o[1] = MF(pa3, PKV(g.c1, g.d1), o[1]); SBAR();
;   float pmax = __builtin_fmaxf(a, b);
;   if (HASX) { auto rr = __builtin_amdgcn_permlane32_swap(__float_as_uint(pmax), __float_as_uint(pmax), false, false); pmax = __builtin_fmaxf(__uint_as_float(rr[0]), __uint_as_float(rr[1])); }
;   return pmax;
; }
; __device__ __forceinline__ void attn_unit(const bf16_t* __restrict__ Qb, const bf16_t* __restrict__ KNh, const bf16_t* __restrict__ KRb, const bf16_t* __restrict__ Vh,
;                                           bf16_t* __restrict__ Ob, int nkeys, char* lds, int tid_in) {
;     ...
;     alA = decide<false>(phaseB<true>(o, pa0, pa1, pa2, pa3, vf, vb0 + vprev, pA0, pA1), pA0, pA1, m_reg, negm);
;     SWAIT(); SWRITE(1, vnext, SO);
.Lmy_h1w:
	s_waitcnt vmcnt(3)
	v_add_u32_e32 v110, s53, v187
	ds_write_b128 v110, v[170:173]
	v_mfma_f32_32x32x16_bf16 v[2:17], v[106:109], v[238:241], v[2:17]
	v_max3_f32 v103, v103, v94, v95
	v_max3_f32 v102, v102, v77, v96
	v_add_f32_e32 v34, v36, v34
	v_add_f32_e32 v35, v211, v212
	v_add_f32_e32 v37, v213, v214
	s_waitcnt vmcnt(2)
	ds_write_b128 v188, v[174:177] offset:37888
	v_mfma_f32_32x32x16_bf16 v[18:33], v[98:101], v[242:245], v[18:33]
	v_max3_f32 v103, v103, v78, v79
	v_max3_f32 v102, v102, v97, v80
	v_add_f32_e32 v35, v35, v37
	v_add_f32_e32 v36, v215, v216
	v_add_f32_e32 v37, v217, v218
	ds_write_b128 v193, v[158:161] offset:38016
	v_add_f32_e32 v34, v35, v34
	v_add_f32_e32 v36, v36, v37
	v_mfma_f32_32x32x16_bf16 v[2:17], v[98:101], v[246:249], v[2:17]
	v_max3_f32 v98, v102, v81, v103
	v_cmp_lt_f32_e32 vcc, s35, v98
	v_add_f32_e32 v34, v36, v34
	v_add_f32_e32 v35, v219, v220
	v_add_f32_e32 v37, v221, v222
	v_add_f32_e32 v35, v35, v37
	v_add_f32_e32 v36, v223, v234
	v_add_f32_e32 v37, v235, v236
	v_add_f32_e32 v34, v35, v34
	v_add_f32_e32 v36, v36, v37
	v_add_f32_e32 v34, v36, v34
	v_add_f32_e32 v194, v34, v194
	s_cbranch_vccnz .LBB0_273

; template <int KB, bool HASY>
; __device__ __forceinline__ void phaseA(f32x16& X0, f32x16& X1, f32x16& Y0, f32x16& Y1, bf16x8& pa0, bf16x8& pa1, bf16x8& pa2, bf16x8& pa3,
;                                        const bf16x8* qr, const f32x16& negm, int kaddr, VFr& vf, int vb, float& l_reg) {
;   SBAR();
;   float ls = 0.f;
;   bf16x8 k0 = rd128<KOFF(KB, 0, 0)>(kaddr), k1 = rd128<KOFF(KB, 1, 0)>(kaddr), k2 = rd128<KOFF(KB, 0, 1)>(kaddr), k3 = rd128<KOFF(KB, 1, 1)>(kaddr);
;   if (HASY) { EXP4(Y0, 0); EXP4(Y0, 4); }
;   SBAR(); WAIT4(k0, k1, k2, k3);
;   bf16x8 k4 = rd128<KOFF(KB, 0, 2)>(kaddr), k5 = rd128<KOFF(KB, 1, 2)>(kaddr), k6 = rd128<KOFF(KB, 0, 3)>(kaddr), k7 = rd128<KOFF(KB, 1, 3)>(kaddr);
;   SBAR();
;   X0 = MF(k0, qr[0], negm); if (HASY) { EXP4(Y0, 8); SUM4(Y0, 0); } SBAR();
;   X1 = MF(k1, qr[0], negm); if (HASY) { EXP4(Y0, 12); SUM4(Y0, 4); } SBAR();
;   X0 = MF(k2, qr[1], X0); if (HASY) { PACK8(Y0, 0, pa0); } SBAR();
;   X1 = MF(k3, qr[1], X1); if (HASY) { EXP4(Y1, 0); SUM4(Y0, 8); } SBAR();
;   WAIT4(k4, k5, k6, k7);
;   bf16x8 k8 = rd128<KOFF(KB, 0, 4)>(kaddr), k9 = rd128<KOFF(KB, 1, 4)>(kaddr), k10 = rd128<KOFF(KB, 0, 5)>(kaddr), k11 = rd128<KOFF(KB, 1, 5)>(kaddr);
;   SBAR();
;   X0 = MF(k4, qr[2], X0); if (HASY) { EXP4(Y1, 4); SUM4(Y0, 12); } SBAR();
;   X1 = MF(k5, qr[2], X1); if (HASY) { PACK8(Y0, 8, pa1); } SBAR();
;   X0 = MF(k6, qr[3], X0); if (HASY) { EXP4(Y1, 8); SUM4(Y1, 0); } SBAR();
;   X1 = MF(k7, qr[3], X1); if (HASY) { EXP4(Y1, 12); SUM4(Y1, 4); } SBAR();
;   WAIT4(k8, k9, k10, k11);
;   SBAR();
;   X0 = MF(k8, qr[4], X0); if (HASY) { PACK8(Y1, 0, pa2); } SBAR();
;   X1 = MF(k9, qr[4], X1); if (HASY) { SUM4(Y1, 8); SUM4(Y1, 12); } SBAR();
;   X0 = MF(k10, qr[5], X0); if (HASY) { PACK8(Y1, 8, pa3); } SBAR();
;   X1 = MF(k11, qr[5], X1); if (HASY) vfr_issue<0>(vf, vb);
;   l_reg += ls;
;   SBAR();
; }
; template <bool HASX>
; __device__ __forceinline__ float phaseB(f32x16* o, bf16x8 pa0, bf16x8 pa1, bf16x8 pa2, bf16x8 pa3, VFr& f, int vb, const f32x16& X0, const f32x16& X1) {
;   SBAR(); VWAIT(f); VFr g; vfr_issue<2>(g, vb); SBAR();
;   float a = 0.f, b = 0.f;
;   o[0] = MF(pa0, PKV(f.a0, f.b0), o[0]); SBAR(); o[1] = MF(pa0, PKV(f.c0, f.d0), o[1]);
;   if (HASX) { a = MX3(X0[0], X0[1], X1[0]); b = MX3(X0[2], X0[3], X1[1]); a = MX3(a, X1[2], X1[3]); b = MX3(b, X0[4], X0[5]); } SBAR();
.Lmy_y249:
	s_mov_b32 s76, s53
	s_mov_b32 s53, s18
	v_add_u32_e32 v0, s53, v192
	ds_read_b128 v[34:37], v184 offset:0x3400
	ds_read_b128 v[38:41], v184 offset:0x4e00
	ds_read_b128 v[42:45], v184 offset:0x3420
	ds_read_b128 v[46:49], v184 offset:0x4e20
	ds_read_b128 v[170:173], v184 offset:0x3440
	ds_read_b128 v[174:177], v184 offset:0x4e40
	ds_read_b128 v[204:207], v184 offset:0x3460
	ds_read_b128 v[208:211], v184 offset:0x4e60
	v_exp_f32_e32 v82, v82
	v_exp_f32_e32 v195, v83
	v_exp_f32_e32 v84, v84
	v_exp_f32_e32 v196, v85
	v_exp_f32_e32 v83, v86
	v_exp_f32_e32 v85, v87
	v_exp_f32_e32 v86, v88
	v_exp_f32_e32 v87, v89
	s_waitcnt lgkmcnt(7)
	v_mfma_f32_32x32x16_bf16 v[114:129], v[34:37], v[150:153], v[50:65]
	v_exp_f32_e32 v88, v90
	v_exp_f32_e32 v89, v91
	v_exp_f32_e32 v90, v92
	v_exp_f32_e32 v91, v93
	s_waitcnt lgkmcnt(6)
	v_mfma_f32_32x32x16_bf16 v[98:113], v[38:41], v[150:153], v[50:65]
	v_exp_f32_e32 v92, v94
	v_exp_f32_e32 v93, v95
	v_exp_f32_e32 v94, v96
	v_exp_f32_e32 v95, v97
	s_waitcnt lgkmcnt(5)
	v_mfma_f32_32x32x16_bf16 v[114:129], v[42:45], v[146:149], v[114:129]
	v_cvt_pk_bf16_f32 v34, v82, v195
	v_cvt_pk_bf16_f32 v35, v84, v196
	v_cvt_pk_bf16_f32 v36, v83, v85
	v_cvt_pk_bf16_f32 v37, v86, v87
	s_waitcnt lgkmcnt(4)
	v_mfma_f32_32x32x16_bf16 v[98:113], v[46:49], v[146:149], v[98:113]
	v_exp_f32_e32 v96, v66
	v_exp_f32_e32 v97, v67
	v_exp_f32_e32 v197, v68
	v_exp_f32_e32 v198, v69
	ds_read_b128 v[38:41], v184 offset:0x3480
	ds_read_b128 v[66:69], v184 offset:0x4e80
	ds_read_b128 v[212:215], v184 offset:0x34a0
	ds_read_b128 v[216:219], v184 offset:0x4ea0
	s_waitcnt lgkmcnt(4)
	v_mfma_f32_32x32x16_bf16 v[114:129], v[170:173], v[142:145], v[114:129]
	v_exp_f32_e32 v199, v70
	v_exp_f32_e32 v200, v71
	v_exp_f32_e32 v201, v72
	v_exp_f32_e32 v202, v73
	v_mfma_f32_32x32x16_bf16 v[98:113], v[174:177], v[142:145], v[98:113]
	v_cvt_pk_bf16_f32 v42, v88, v89
	v_cvt_pk_bf16_f32 v43, v90, v91
	v_cvt_pk_bf16_f32 v44, v92, v93
	v_cvt_pk_bf16_f32 v45, v94, v95
	v_mfma_f32_32x32x16_bf16 v[114:129], v[204:207], v[138:141], v[114:129]
	v_exp_f32_e32 v203, v74
	v_exp_f32_e32 v204, v75
	v_exp_f32_e32 v205, v76
	v_exp_f32_e32 v206, v77
	v_mfma_f32_32x32x16_bf16 v[98:113], v[208:211], v[138:141], v[98:113]
	v_exp_f32_e32 v207, v78
	v_exp_f32_e32 v208, v79
	v_exp_f32_e32 v209, v80
	v_exp_f32_e32 v210, v81
	s_waitcnt lgkmcnt(0)
	s_nop 0
	v_mfma_f32_32x32x16_bf16 v[114:129], v[38:41], v[134:137], v[114:129]
	v_cvt_pk_bf16_f32 v46, v96, v97
	v_cvt_pk_bf16_f32 v47, v197, v198
	v_cvt_pk_bf16_f32 v48, v199, v200
	v_cvt_pk_bf16_f32 v49, v201, v202
	v_mfma_f32_32x32x16_bf16 v[98:113], v[66:69], v[134:137], v[98:113]
	v_mfma_f32_32x32x16_bf16 v[114:129], v[212:215], v[130:133], v[114:129]
	v_cvt_pk_bf16_f32 v38, v203, v204
	v_cvt_pk_bf16_f32 v39, v205, v206
	v_cvt_pk_bf16_f32 v40, v207, v208
	v_cvt_pk_bf16_f32 v41, v209, v210
	ds_read_b64_tr_b16 v[78:79], v0 offset:0
	ds_read_b64_tr_b16 v[80:81], v0 offset:0x400
	ds_read_b64_tr_b16 v[74:75], v0 offset:0x200
	v_mfma_f32_32x32x16_bf16 v[98:113], v[216:219], v[130:133], v[98:113]
	ds_read_b64_tr_b16 v[76:77], v0 offset:0x600
	ds_read_b64_tr_b16 v[70:71], v0 offset:0x800
	ds_read_b64_tr_b16 v[72:73], v0 offset:0xc00
	ds_read_b64_tr_b16 v[66:67], v0 offset:0xa00
	ds_read_b64_tr_b16 v[68:69], v0 offset:0xe00
	s_add_i32 s18, s52, 0xffffe000
	s_mov_b32 s46, s66
	s_mov_b32 s47, s67
	buffer_load_dwordx4 v[170:173], v185, s[64:67], s18 offen
	buffer_load_dwordx4 v[174:177], v185, s[44:47], s18 offen
	s_waitcnt lgkmcnt(0)
	ds_read_b64_tr_b16 v[212:213], v0 offset:0x1000
	ds_read_b64_tr_b16 v[214:215], v0 offset:0x1400
	ds_read_b64_tr_b16 v[216:217], v0 offset:0x1200
	ds_read_b64_tr_b16 v[218:219], v0 offset:0x1600
	ds_read_b64_tr_b16 v[220:221], v0 offset:0x1800
	ds_read_b64_tr_b16 v[222:223], v0 offset:0x1c00
	ds_read_b64_tr_b16 v[228:229], v0 offset:0x1a00
	ds_read_b64_tr_b16 v[230:231], v0 offset:0x1e00
	s_nop 0
	v_mfma_f32_32x32x16_bf16 v[18:33], v[34:37], v[78:81], v[18:33]
	v_add_f32_e32 v238, v82, v195
	v_add_f32_e32 v239, v84, v196
	v_add_f32_e32 v240, v83, v85
	v_add_f32_e32 v241, v86, v87
	v_add_f32_e32 v238, v238, v239
	v_add_f32_e32 v240, v240, v241
	v_mfma_f32_32x32x16_bf16 v[2:17], v[34:37], v[74:77], v[2:17]
	v_max_f32_e32 v34, v114, v115
	v_max3_f32 v35, v116, v117, v99
	v_max3_f32 v34, v34, v98, v100
	v_max3_f32 v35, v35, v118, v119
	v_mfma_f32_32x32x16_bf16 v[18:33], v[42:45], v[70:73], v[18:33]
	v_max3_f32 v34, v34, v101, v120
	v_max3_f32 v35, v35, v102, v103
	v_add_f32_e32 v238, v240, v238
	v_add_f32_e32 v239, v88, v89
	v_add_f32_e32 v241, v90, v91
	v_mfma_f32_32x32x16_bf16 v[2:17], v[42:45], v[66:69], v[2:17]
	v_max3_f32 v34, v34, v121, v104
	v_max3_f32 v34, v34, v105, v124
	v_max3_f32 v35, v35, v122, v123
	v_add_f32_e32 v239, v239, v241
	v_add_f32_e32 v240, v92, v93
	v_add_f32_e32 v241, v94, v95
	s_waitcnt lgkmcnt(0)
	s_nop 0
	v_mfma_f32_32x32x16_bf16 v[18:33], v[46:49], v[212:215], v[18:33]
	v_max3_f32 v34, v34, v125, v108
	v_max3_f32 v35, v35, v106, v107
	v_add_f32_e32 v238, v239, v238
	v_add_f32_e32 v240, v240, v241
	s_waitcnt vmcnt(3)
	v_add_u32_e32 v67, s69, v187
	ds_write_b128 v67, v[162:165]
	v_mfma_f32_32x32x16_bf16 v[2:17], v[46:49], v[216:219], v[2:17]
	v_max3_f32 v34, v34, v109, v128
	v_max3_f32 v35, v35, v126, v127
	v_add_f32_e32 v238, v240, v238
	v_add_f32_e32 v239, v96, v97
	v_add_f32_e32 v241, v197, v198
	s_waitcnt vmcnt(2)
	ds_write_b128 v188, v[166:169] offset:24576
	v_mfma_f32_32x32x16_bf16 v[18:33], v[38:41], v[220:223], v[18:33]
	v_max3_f32 v34, v34, v129, v112
	v_max3_f32 v35, v35, v110, v111
	v_add_f32_e32 v239, v239, v241
	v_add_f32_e32 v240, v199, v200
	v_add_f32_e32 v241, v201, v202
	v_add_f32_e32 v238, v239, v238
	v_add_f32_e32 v240, v240, v241
	v_mfma_f32_32x32x16_bf16 v[2:17], v[38:41], v[228:231], v[2:17]
	v_max3_f32 v34, v34, v113, v35
	v_cmp_lt_f32_e32 vcc, s35, v34
	v_add_f32_e32 v238, v240, v238
	v_add_f32_e32 v239, v203, v204
	v_add_f32_e32 v241, v205, v206
	v_add_f32_e32 v239, v239, v241
	v_add_f32_e32 v240, v207, v208
	v_add_f32_e32 v241, v209, v210
	v_add_f32_e32 v238, v239, v238
	v_add_f32_e32 v240, v240, v241
	v_add_f32_e32 v238, v240, v238
	v_add_f32_e32 v194, v194, v238
	s_cbranch_vccnz .Lmy_y272
; template <int KB, bool HASY>
; __device__ __forceinline__ void phaseA(f32x16& X0, f32x16& X1, f32x16& Y0, f32x16& Y1, bf16x8& pa0, bf16x8& pa1, bf16x8& pa2, bf16x8& pa3,
;                                        const bf16x8* qr, const f32x16& negm, int kaddr, VFr& vf, int vb, float& l_reg) {
;   SBAR();
;   float ls = 0.f;
;   bf16x8 k0 = rd128<KOFF(KB, 0, 0)>(kaddr), k1 = rd128<KOFF(KB, 1, 0)>(kaddr), k2 = rd128<KOFF(KB, 0, 1)>(kaddr), k3 = rd128<KOFF(KB, 1, 1)>(kaddr);
;   if (HASY) { EXP4(Y0, 0); EXP4(Y0, 4); }
;   SBAR(); WAIT4(k0, k1, k2, k3);
;   bf16x8 k4 = rd128<KOFF(KB, 0, 2)>(kaddr), k5 = rd128<KOFF(KB, 1, 2)>(kaddr), k6 = rd128<KOFF(KB, 0, 3)>(kaddr), k7 = rd128<KOFF(KB, 1, 3)>(kaddr);
;   SBAR();
;   X0 = MF(k0, qr[0], negm); if (HASY) { EXP4(Y0, 8); SUM4(Y0, 0); } SBAR();
;   X1 = MF(k1, qr[0], negm); if (HASY) { EXP4(Y0, 12); SUM4(Y0, 4); } SBAR();
;   X0 = MF(k2, qr[1], X0); if (HASY) { PACK8(Y0, 0, pa0); } SBAR();
;   X1 = MF(k3, qr[1], X1); if (HASY) { EXP4(Y1, 0); SUM4(Y0, 8); } SBAR();
;   WAIT4(k4, k5, k6, k7);
;   bf16x8 k8 = rd128<KOFF(KB, 0, 4)>(kaddr), k9 = rd128<KOFF(KB, 1, 4)>(kaddr), k10 = rd128<KOFF(KB, 0, 5)>(kaddr), k11 = rd128<KOFF(KB, 1, 5)>(kaddr);
;   SBAR();
;   X0 = MF(k4, qr[2], X0); if (HASY) { EXP4(Y1, 4); SUM4(Y0, 12); } SBAR();
;   X1 = MF(k5, qr[2], X1); if (HASY) { PACK8(Y0, 8, pa1); } SBAR();
;   X0 = MF(k6, qr[3], X0); if (HASY) { EXP4(Y1, 8); SUM4(Y1, 0); } SBAR();
;   X1 = MF(k7, qr[3], X1); if (HASY) { EXP4(Y1, 12); SUM4(Y1, 4); } SBAR();
;   WAIT4(k8, k9, k10, k11);
;   SBAR();
;   X0 = MF(k8, qr[4], X0); if (HASY) { PACK8(Y1, 0, pa2); } SBAR();
;   X1 = MF(k9, qr[4], X1); if (HASY) { SUM4(Y1, 8); SUM4(Y1, 12); } SBAR();
;   X0 = MF(k10, qr[5], X0); if (HASY) { PACK8(Y1, 8, pa3); } SBAR();
;   X1 = MF(k11, qr[5], X1); if (HASY) vfr_issue<0>(vf, vb);
;   l_reg += ls;
;   SBAR();
; }
; template <bool HASX>
; __device__ __forceinline__ float phaseB(f32x16* o, bf16x8 pa0, bf16x8 pa1, bf16x8 pa2, bf16x8 pa3, VFr& f, int vb, const f32x16& X0, const f32x16& X1) {
;   SBAR(); VWAIT(f); VFr g; vfr_issue<2>(g, vb); SBAR();
;   float a = 0.f, b = 0.f;
;   o[0] = MF(pa0, PKV(f.a0, f.b0), o[0]); SBAR(); o[1] = MF(pa0, PKV(f.c0, f.d0), o[1]);
;   if (HASX) { a = MX3(X0[0], X0[1], X1[0]); b = MX3(X0[2], X0[3], X1[1]); a = MX3(a, X1[2], X1[3]); b = MX3(b, X0[4], X0[5]); } SBAR();
.Lmy_y259:
	v_add_u32_e32 v237, s76, v192
	s_waitcnt lgkmcnt(0)
	s_barrier
	ds_read_b128 v[66:69], v184 offset:0
	ds_read_b128 v[212:215], v184 offset:0x1a00
	ds_read_b128 v[216:219], v184 offset:32
	v_exp_f32_e32 v195, v114
	v_exp_f32_e32 v197, v115
	v_exp_f32_e32 v198, v116
	v_exp_f32_e32 v201, v117
	v_exp_f32_e32 v196, v118
	v_exp_f32_e32 v199, v119
	v_exp_f32_e32 v200, v120
	v_exp_f32_e32 v202, v121
	ds_read_b128 v[118:121], v184 offset:0x1a20
	ds_read_b128 v[220:223], v184 offset:64
	ds_read_b128 v[228:231], v184 offset:0x1a40
	ds_read_b128 v[238:241], v184 offset:0x60
	ds_read_b128 v[242:245], v184 offset:0x1a60
	s_waitcnt lgkmcnt(7)
	v_mfma_f32_32x32x16_bf16 v[82:97], v[66:69], v[150:153], v[50:65]
	v_exp_f32_e32 v203, v122
	v_exp_f32_e32 v204, v123
	v_exp_f32_e32 v205, v124
	v_exp_f32_e32 v206, v125
	s_waitcnt lgkmcnt(6)
	v_mfma_f32_32x32x16_bf16 v[66:81], v[212:215], v[150:153], v[50:65]
	v_exp_f32_e32 v207, v126
	v_exp_f32_e32 v208, v127
	v_exp_f32_e32 v209, v128
	v_exp_f32_e32 v210, v129
	s_waitcnt lgkmcnt(5)
	v_mfma_f32_32x32x16_bf16 v[82:97], v[216:219], v[146:149], v[82:97]
	v_cvt_pk_bf16_f32 v114, v195, v197
	v_cvt_pk_bf16_f32 v115, v198, v201
	v_cvt_pk_bf16_f32 v116, v196, v199
	v_cvt_pk_bf16_f32 v117, v200, v202
	s_waitcnt lgkmcnt(4)
	v_mfma_f32_32x32x16_bf16 v[66:81], v[118:121], v[146:149], v[66:81]
	v_exp_f32_e32 v211, v98
	v_exp_f32_e32 v212, v99
	v_exp_f32_e32 v213, v100
	v_exp_f32_e32 v214, v101
	ds_read_b128 v[98:101], v184 offset:0x80
	ds_read_b128 v[118:121], v184 offset:0x1a80
	ds_read_b128 v[122:125], v184 offset:0xa0
	ds_read_b128 v[246:249], v184 offset:0x1aa0
	s_waitcnt lgkmcnt(4)
	v_mfma_f32_32x32x16_bf16 v[82:97], v[220:223], v[142:145], v[82:97]
	v_exp_f32_e32 v215, v102
	v_exp_f32_e32 v216, v103
	v_exp_f32_e32 v217, v104
	v_exp_f32_e32 v218, v105
	v_mfma_f32_32x32x16_bf16 v[66:81], v[228:231], v[142:145], v[66:81]
	v_cvt_pk_bf16_f32 v102, v203, v204
	v_cvt_pk_bf16_f32 v103, v205, v206
	v_cvt_pk_bf16_f32 v104, v207, v208
	v_cvt_pk_bf16_f32 v105, v209, v210
	v_mfma_f32_32x32x16_bf16 v[82:97], v[238:241], v[138:141], v[82:97]
	v_exp_f32_e32 v219, v106
	v_exp_f32_e32 v220, v107
	v_exp_f32_e32 v221, v108
	v_exp_f32_e32 v222, v109
	v_mfma_f32_32x32x16_bf16 v[66:81], v[242:245], v[138:141], v[66:81]
	v_exp_f32_e32 v223, v110
	v_exp_f32_e32 v234, v111
	v_exp_f32_e32 v235, v112
	v_exp_f32_e32 v236, v113
	s_waitcnt lgkmcnt(0)
	s_nop 0
	v_mfma_f32_32x32x16_bf16 v[82:97], v[98:101], v[134:137], v[82:97]
	v_cvt_pk_bf16_f32 v106, v211, v212
	v_cvt_pk_bf16_f32 v107, v213, v214
	v_cvt_pk_bf16_f32 v108, v215, v216
	v_cvt_pk_bf16_f32 v109, v217, v218
	v_mfma_f32_32x32x16_bf16 v[66:81], v[118:121], v[134:137], v[66:81]
	v_mfma_f32_32x32x16_bf16 v[82:97], v[122:125], v[130:133], v[82:97]
	v_cvt_pk_bf16_f32 v98, v219, v220
	v_cvt_pk_bf16_f32 v99, v221, v222
	v_cvt_pk_bf16_f32 v100, v223, v234
	v_cvt_pk_bf16_f32 v101, v235, v236
	ds_read_b64_tr_b16 v[126:127], v237 offset:0
	ds_read_b64_tr_b16 v[128:129], v237 offset:0x400
	ds_read_b64_tr_b16 v[122:123], v237 offset:0x200
	v_mfma_f32_32x32x16_bf16 v[66:81], v[246:249], v[130:133], v[66:81]
	ds_read_b64_tr_b16 v[124:125], v237 offset:0x600
	ds_read_b64_tr_b16 v[118:119], v237 offset:0x800
	ds_read_b64_tr_b16 v[120:121], v237 offset:0xc00
	ds_read_b64_tr_b16 v[110:111], v237 offset:0xa00
	ds_read_b64_tr_b16 v[112:113], v237 offset:0xe00
	s_cmp_ge_u32 s39, s38
	s_cselect_b64 s[18:19], -1, 0
	s_and_b64 vcc, exec, s[18:19]
	s_cbranch_vccnz .Lmy_y263
	s_mov_b32 s46, s66
	s_mov_b32 s47, s67
	buffer_load_dwordx4 v[162:165], v185, s[64:67], s52 offen
	buffer_load_dwordx4 v[166:169], v185, s[44:47], s52 offen
.Lmy_y263:
	s_waitcnt lgkmcnt(0)
	ds_read_b64_tr_b16 v[228:229], v237 offset:0x1000
	ds_read_b64_tr_b16 v[230:231], v237 offset:0x1400
	ds_read_b64_tr_b16 v[238:239], v237 offset:0x1200
	ds_read_b64_tr_b16 v[240:241], v237 offset:0x1600
	ds_read_b64_tr_b16 v[242:243], v237 offset:0x1800
	ds_read_b64_tr_b16 v[244:245], v237 offset:0x1c00
	ds_read_b64_tr_b16 v[246:247], v237 offset:0x1a00
	ds_read_b64_tr_b16 v[248:249], v237 offset:0x1e00
	s_nop 0
	v_mfma_f32_32x32x16_bf16 v[18:33], v[114:117], v[126:129], v[18:33]
	v_add_f32_e32 v34, v195, v197
	v_add_f32_e32 v35, v198, v201
	v_add_f32_e32 v36, v196, v199
	v_add_f32_e32 v37, v200, v202
	v_add_f32_e32 v34, v34, v35
	v_add_f32_e32 v36, v36, v37
	v_mfma_f32_32x32x16_bf16 v[2:17], v[114:117], v[122:125], v[2:17]
	v_max_f32_e32 v114, v82, v83
	v_max3_f32 v115, v84, v85, v67
	v_max3_f32 v114, v114, v66, v68
	v_max3_f32 v115, v115, v86, v87
	v_mfma_f32_32x32x16_bf16 v[18:33], v[102:105], v[118:121], v[18:33]
	v_max3_f32 v114, v114, v69, v88
	v_max3_f32 v115, v115, v70, v71
	v_add_f32_e32 v34, v36, v34
	v_add_f32_e32 v35, v203, v204
	v_add_f32_e32 v37, v205, v206
	v_mfma_f32_32x32x16_bf16 v[2:17], v[102:105], v[110:113], v[2:17]
	v_max3_f32 v102, v114, v89, v72
	v_max3_f32 v103, v115, v90, v91
	v_max3_f32 v102, v102, v73, v92
	v_add_f32_e32 v35, v35, v37
	v_add_f32_e32 v36, v207, v208
	v_add_f32_e32 v37, v209, v210
	s_waitcnt lgkmcnt(0)
	s_nop 0
	v_mfma_f32_32x32x16_bf16 v[18:33], v[106:109], v[228:231], v[18:33]
	v_max3_f32 v103, v103, v74, v75
	v_max3_f32 v102, v102, v93, v76
	v_add_f32_e32 v34, v35, v34
	v_add_f32_e32 v36, v36, v37
	s_cmp_ge_u32 s39, s38
	s_cbranch_scc0 .Lmy_yh1w
	s_waitcnt vmcnt(0)
.Lmy_yh1w:
	s_waitcnt vmcnt(3)
	v_add_u32_e32 v110, s53, v187
	ds_write_b128 v110, v[170:173]
	v_mfma_f32_32x32x16_bf16 v[2:17], v[106:109], v[238:241], v[2:17]
	v_max3_f32 v103, v103, v94, v95
	v_max3_f32 v102, v102, v77, v96
	v_add_f32_e32 v34, v36, v34
	v_add_f32_e32 v35, v211, v212
	v_add_f32_e32 v37, v213, v214
	s_waitcnt vmcnt(2)
	ds_write_b128 v188, v[174:177] offset:37888
	v_mfma_f32_32x32x16_bf16 v[18:33], v[98:101], v[242:245], v[18:33]
	v_max3_f32 v103, v103, v78, v79
	v_max3_f32 v102, v102, v97, v80
	v_add_f32_e32 v35, v35, v37
	v_add_f32_e32 v36, v215, v216
	v_add_f32_e32 v37, v217, v218
	v_add_f32_e32 v34, v35, v34
	v_add_f32_e32 v36, v36, v37
	v_mfma_f32_32x32x16_bf16 v[2:17], v[98:101], v[246:249], v[2:17]
	v_max3_f32 v98, v102, v81, v103
	v_cmp_lt_f32_e32 vcc, s35, v98
	v_add_f32_e32 v34, v36, v34
	v_add_f32_e32 v35, v219, v220
	v_add_f32_e32 v37, v221, v222
	v_add_f32_e32 v35, v35, v37
	v_add_f32_e32 v36, v223, v234
	v_add_f32_e32 v37, v235, v236
	v_add_f32_e32 v34, v35, v34
	v_add_f32_e32 v36, v36, v37
	v_add_f32_e32 v34, v36, v34
	v_add_f32_e32 v194, v34, v194
	s_cbranch_vccnz .Lmy_y273
